# barrier-shadow filler: first R4 iteration (context rows) runs between arrive and wait of the ff1b->ff2b barrier; final R4 starts at its second iteration
# speedup vs baseline: 1.0022x; 1.0022x over previous
.LBB0_789:
	s_mov_b32 s32, 0
	v_readlane_b32 s8, v254, 39
	v_readlane_b32 s9, v254, 40
	s_cmp_gt_i32 s9, 10
	s_cselect_b64 s[8:9], -1, 0
	s_and_b64 s[6:7], s[6:7], s[8:9]
	s_andn2_b64 vcc, exec, s[6:7]
	s_cbranch_vccnz .LBB0_843
	s_waitcnt vmcnt(0)
	s_barrier
	s_mov_b32 s32, 1
	s_mov_b64 s[6:7], exec
	v_readlane_b32 s10, v254, 2
	v_readlane_b32 s11, v254, 3
	s_nop 1
	s_and_b64 s[10:11], s[6:7], s[10:11]
	s_mov_b64 exec, s[10:11]
	s_cbranch_execz .Lff1b_arrive_join
	s_getreg_b32 s12, hwreg(HW_REG_XCC_ID, 0, 4)
	v_mov_b32_e32 v2, 0x23fc0
	ds_read_b64 v[2:3], v2
	s_lshl_b32 s12, s12, 6
	s_add_u32 s14, s62, 0x409000
	s_addc_u32 s15, s63, 0
	v_mov_b32_e32 v4, s12
	v_mov_b32_e32 v5, 1
	global_atomic_add v6, v4, v5, s[14:15] sc0
	s_waitcnt vmcnt(0) lgkmcnt(0)
	v_add_u32_e32 v6, 1, v6
	v_cmp_eq_u32_e32 vcc, v6, v2
	s_cbranch_vccz .Lff1b_arrive_join
	buffer_wbl2 sc1
	s_waitcnt vmcnt(0)
	v_mov_b32_e32 v4, 0x400
	global_atomic_add v4, v5, s[14:15]

.LBB0_860:
	s_cmp_eq_u32 s32, 0
	s_cbranch_scc1 .Lff1b_nowait
	s_mov_b32 s32, 0
	v_writelane_b32 v255, s4, 40
	v_writelane_b32 v255, s5, 41
	v_writelane_b32 v255, s26, 42
	v_writelane_b32 v255, s27, 43
	v_writelane_b32 v255, s46, 44
	v_writelane_b32 v255, s47, 45
	s_mov_b64 s[4:5], exec
	v_readlane_b32 s26, v254, 2
	v_readlane_b32 s27, v254, 3
	s_nop 1
	s_and_b64 s[26:27], s[4:5], s[26:27]
	s_mov_b64 exec, s[26:27]
	s_cbranch_execz .Lff1b_wait_join
	v_mov_b32_e32 v168, 0x23fc4
	ds_read_b32 v169, v168
	s_add_u32 s46, s62, 0x409000
	s_addc_u32 s47, s63, 0
	v_mov_b32_e32 v168, 0x400
	s_mov_b32 s26, 0
	buffer_inv sc1

.Llb865_arrdone:
	s_mov_b64 exec, s[8:9]
	v_writelane_b32 v255, s0, 40
	v_writelane_b32 v255, s1, 41
	v_writelane_b32 v255, s2, 42
	v_writelane_b32 v255, s3, 43
	v_writelane_b32 v255, s6, 44
	v_writelane_b32 v255, s7, 45
	v_writelane_b32 v255, s25, 46
	v_writelane_b32 v255, s26, 47
	v_writelane_b32 v255, s27, 48
	v_writelane_b32 v255, s28, 49
	v_writelane_b32 v255, s49, 50
	v_mov_b32_e32 v222, v1
	v_mov_b32_e32 v223, v138
	v_mov_b32_e32 v224, v139
	v_mov_b32_e32 v225, v140
	v_mov_b32_e32 v226, v141
	v_mov_b32_e32 v227, v142
	v_mov_b32_e32 v228, v143
	v_mov_b32_e32 v229, v144
	v_mov_b32_e32 v230, v145
	v_mov_b32_e32 v231, v154
	v_mov_b32_e32 v232, v155
	v_mov_b32_e32 v233, v156
	v_mov_b32_e32 v234, v157
	v_mov_b32_e32 v235, v158
	v_mov_b32_e32 v236, v159
	v_mov_b32_e32 v237, v160
	s_movk_i32 s9, 0x2000
	v_mbcnt_lo_u32_b32 v1, -1, 0
	v_mbcnt_hi_u32_b32 v3, -1, v1
	v_and_b32_e32 v1, 64, v3
	v_add_u32_e32 v4, 64, v1
	v_xor_b32_e32 v1, 1, v3
	v_cmp_lt_i32_e32 vcc, v1, v4
	v_xor_b32_e32 v6, 2, v3
	s_lshl_b32 s2, s44, 1
	v_cndmask_b32_e32 v1, v3, v1, vcc
	v_cmp_lt_i32_e32 vcc, v6, v4
	v_lshlrev_b32_e32 v2, 3, v191
	v_mov_b32_e32 v5, 0
	v_cndmask_b32_e32 v6, v3, v6, vcc
	v_lshlrev_b32_e32 v61, 2, v6
	v_xor_b32_e32 v6, 4, v3
	v_cmp_lt_i32_e32 vcc, v6, v4
	v_or_b32_e32 v8, 0x400, v2
	s_ashr_i32 s3, s2, 31
	v_cndmask_b32_e32 v6, v3, v6, vcc
	v_lshlrev_b32_e32 v75, 2, v6
	v_xor_b32_e32 v6, 8, v3
	v_cmp_lt_i32_e32 vcc, v6, v4
	v_or_b32_e32 v10, 0x600, v2
	v_lshlrev_b32_e32 v12, 2, v8
	v_cndmask_b32_e32 v6, v3, v6, vcc
	v_mov_b32_e32 v13, v5
	s_lshl_b64 s[0:1], s[2:3], 12
	v_lshlrev_b32_e32 v77, 2, v6
	v_xor_b32_e32 v6, 16, v3
	v_lshl_add_u64 v[52:53], s[58:59], 0, v[12:13]
	v_lshlrev_b32_e32 v12, 2, v10
	s_add_u32 s0, s62, s0
	v_cmp_lt_i32_e32 vcc, v6, v4
	v_lshl_add_u64 v[54:55], s[58:59], 0, v[12:13]
	v_lshlrev_b32_e32 v12, 4, v191
	s_addc_u32 s1, s63, s1
	v_cndmask_b32_e32 v6, v3, v6, vcc
	v_lshl_add_u64 v[12:13], s[0:1], 0, v[12:13]
	s_mov_b64 s[0:1], 0x10800000
	s_ashr_i32 s49, s48, 31
	v_lshlrev_b32_e32 v94, 2, v6
	v_xor_b32_e32 v6, 32, v3
	v_lshl_add_u64 v[56:57], v[12:13], 0, s[0:1]
	s_lshl_b64 s[4:5], s[48:49], 12
	s_lshl_b64 s[0:1], s[2:3], 13
	v_cmp_lt_i32_e32 vcc, v6, v4
	s_add_u32 s0, s60, s0
	v_lshlrev_b32_e32 v4, 5, v191
	v_cndmask_b32_e32 v3, v3, v6, vcc
	v_or_b32_e32 v6, 0x200, v2
	s_addc_u32 s1, s61, s1
	v_lshlrev_b32_e32 v1, 2, v1
	v_lshlrev_b32_e32 v95, 2, v3
	v_lshl_add_u64 v[50:51], s[58:59], 0, v[4:5]
	v_lshl_add_u64 v[58:59], s[0:1], 0, v[4:5]
	s_lshl_b64 s[6:7], s[48:49], 13
	s_movk_i32 s3, 0x1000
	s_mov_b32 s12, 0x4001000
	v_lshlrev_b32_e32 v96, 2, v2
	v_lshlrev_b32_e32 v97, 2, v6
	v_lshlrev_b32_e32 v98, 2, v8
	v_lshlrev_b32_e32 v99, 2, v10
	s_mov_b32 s8, 0x3a000000
	s_mov_b32 s13, 0x800000
	s_movk_i32 s14, 0x3000
	v_mov_b32_e32 v60, 0x358637bd
	v_add_co_u32_e32 v30, vcc, 0x4000000, v56
	global_load_dwordx4 v[22:25], v[56:57], off
	global_load_dwordx4 v[18:21], v[56:57], off offset:1024
	global_load_dwordx4 v[14:17], v[56:57], off offset:2048
	global_load_dwordx4 v[10:13], v[56:57], off offset:3072
	v_addc_co_u32_e32 v31, vcc, 0, v57, vcc
	v_add_co_u32_e32 v32, vcc, s3, v56
	global_load_dwordx4 v[2:5], v[50:51], off offset:16
	global_load_dwordx4 v[6:9], v[50:51], off
	v_addc_co_u32_e32 v33, vcc, 0, v57, vcc
	global_load_dwordx4 v[78:81], v[30:31], off
	global_load_dwordx4 v[42:45], v[30:31], off offset:1024
	global_load_dwordx4 v[34:37], v[30:31], off offset:2048
	global_load_dwordx4 v[26:29], v[30:31], off offset:3072
	global_load_dwordx4 v[82:85], v[32:33], off
	global_load_dwordx4 v[100:103], v[32:33], off offset:1024
	global_load_dwordx4 v[104:107], v[32:33], off offset:2048
	global_load_dwordx4 v[108:111], v[32:33], off offset:3072
	v_add_co_u32_e32 v66, vcc, s12, v56
	v_add_co_u32_e64 v64, s[0:1], s9, v58
	s_nop 0
	v_addc_co_u32_e32 v67, vcc, 0, v57, vcc
	global_load_dwordx4 v[112:115], v[66:67], off
	global_load_dwordx4 v[46:49], v[66:67], off offset:1024
	global_load_dwordx4 v[38:41], v[66:67], off offset:2048
	global_load_dwordx4 v[30:33], v[66:67], off offset:3072
	v_addc_co_u32_e64 v65, s[0:1], 0, v59, s[0:1]
	v_add_co_u32_e64 v62, s[0:1], s14, v58
	s_add_i32 s10, s2, 0xffffe000
	s_nop 0
	v_addc_co_u32_e64 v63, s[0:1], 0, v59, s[0:1]
	s_lshr_b32 s0, s10, 10
	s_add_i32 s0, s0, 1
	s_cmpk_gt_i32 s2, 0x1fff
	s_cselect_b32 s0, s0, 0
	s_mul_hi_u32 s1, s0, 0xc000
	s_mul_i32 s0, s0, 0xc000
	s_add_u32 s0, s62, s0
	s_addc_u32 s1, s63, s1
	s_add_u32 s10, s0, 0xa000
	s_addc_u32 s11, s1, 0
	global_load_dwordx4 v[116:119], v96, s[10:11] offset:16
	global_load_dwordx4 v[120:123], v96, s[10:11]
	s_add_i32 s2, s2, s48
	v_lshl_add_u64 v[56:57], v[56:57], 0, s[4:5]
	s_cmpk_lt_i32 s2, 0x4000
	s_waitcnt vmcnt(0)
	v_and_b32_e32 v125, 0xffff0000, v22
	v_lshlrev_b32_e32 v124, 16, v22
	v_lshlrev_b32_e32 v126, 16, v23
	v_and_b32_e32 v127, 0xffff0000, v23
	v_lshlrev_b32_e32 v70, 16, v16
	v_and_b32_e32 v71, 0xffff0000, v16
	v_lshlrev_b32_e32 v72, 16, v17
	v_and_b32_e32 v73, 0xffff0000, v17
	v_lshlrev_b32_e32 v16, 16, v12
	v_and_b32_e32 v207, 0xffff0000, v82
	v_and_b32_e32 v17, 0xffff0000, v12
	v_mov_b32_e32 v137, v125
	v_lshlrev_b32_e32 v206, 16, v82
	v_lshlrev_b32_e32 v22, 16, v110
	v_and_b32_e32 v23, 0xffff0000, v110
	v_mov_b32_e32 v136, v207
	v_lshlrev_b32_e32 v86, 16, v18
	v_and_b32_e32 v87, 0xffff0000, v18
	v_lshlrev_b32_e32 v88, 16, v19
	v_and_b32_e32 v89, 0xffff0000, v19
	v_lshlrev_b32_e32 v90, 16, v20
	v_and_b32_e32 v91, 0xffff0000, v20
	v_lshlrev_b32_e32 v92, 16, v21
	v_and_b32_e32 v93, 0xffff0000, v21
	v_mov_b32_e32 v135, v124
	v_pk_mul_f32 v[170:171], v[16:17], v[16:17]
	v_lshlrev_b32_e32 v208, 16, v83
	v_lshlrev_b32_e32 v214, 16, v100
	v_and_b32_e32 v215, 0xffff0000, v100
	v_lshlrev_b32_e32 v216, 16, v101
	v_and_b32_e32 v217, 0xffff0000, v101
	v_lshlrev_b32_e32 v218, 16, v102
	v_and_b32_e32 v219, 0xffff0000, v102
	v_lshlrev_b32_e32 v220, 16, v103
	v_and_b32_e32 v221, 0xffff0000, v103
	v_lshlrev_b32_e32 v18, 16, v108
	v_and_b32_e32 v19, 0xffff0000, v108
	v_lshlrev_b32_e32 v20, 16, v109
	v_and_b32_e32 v21, 0xffff0000, v109
	v_lshlrev_b32_e32 v100, 16, v112
	v_and_b32_e32 v101, 0xffff0000, v112
	v_lshlrev_b32_e32 v102, 16, v113
	v_and_b32_e32 v103, 0xffff0000, v113
	v_mov_b32_e32 v134, v206
	v_pk_mul_f32 v[108:109], v[22:23], v[22:23]
	v_pk_mul_f32 v[112:113], v[136:137], v[136:137]
	v_mov_b32_e32 v139, v126
	v_mov_b32_e32 v203, v170
	v_and_b32_e32 v209, 0xffff0000, v83
	v_mov_b32_e32 v138, v208
	v_mov_b32_e32 v202, v108
	v_mov_b32_e32 v170, v109
	v_pk_fma_f32 v[108:109], v[134:135], v[134:135], v[112:113]
	v_lshlrev_b32_e32 v128, 16, v24
	v_mov_b32_e32 v141, v127
	v_lshlrev_b32_e32 v210, 16, v84
	v_mov_b32_e32 v140, v209
	v_pk_fma_f32 v[108:109], v[138:139], v[138:139], v[108:109]
	v_and_b32_e32 v129, 0xffff0000, v24
	v_mov_b32_e32 v143, v128
	v_and_b32_e32 v211, 0xffff0000, v84
	v_mov_b32_e32 v142, v210
	v_pk_fma_f32 v[108:109], v[140:141], v[140:141], v[108:109]
	v_lshlrev_b32_e32 v130, 16, v25
	v_mov_b32_e32 v145, v129
	v_lshlrev_b32_e32 v212, 16, v85
	v_mov_b32_e32 v144, v211
	v_pk_fma_f32 v[108:109], v[142:143], v[142:143], v[108:109]
	v_and_b32_e32 v131, 0xffff0000, v25
	v_mov_b32_e32 v147, v130
	v_and_b32_e32 v213, 0xffff0000, v85
	v_mov_b32_e32 v146, v212
	v_pk_fma_f32 v[108:109], v[144:145], v[144:145], v[108:109]
	v_mov_b32_e32 v133, v131
	v_mov_b32_e32 v132, v213
	v_pk_fma_f32 v[108:109], v[146:147], v[146:147], v[108:109]
	v_mov_b32_e32 v149, v86
	v_mov_b32_e32 v148, v214
	v_pk_fma_f32 v[108:109], v[132:133], v[132:133], v[108:109]
	v_mov_b32_e32 v151, v87
	v_mov_b32_e32 v150, v215
	v_pk_fma_f32 v[108:109], v[148:149], v[148:149], v[108:109]
	v_mov_b32_e32 v153, v88
	v_mov_b32_e32 v152, v216
	v_pk_fma_f32 v[108:109], v[150:151], v[150:151], v[108:109]
	v_mov_b32_e32 v155, v89
	v_mov_b32_e32 v154, v217
	v_pk_fma_f32 v[108:109], v[152:153], v[152:153], v[108:109]
	v_mov_b32_e32 v157, v90
	v_mov_b32_e32 v156, v218
	v_pk_fma_f32 v[108:109], v[154:155], v[154:155], v[108:109]
	v_mov_b32_e32 v159, v91
	v_mov_b32_e32 v158, v219
	v_pk_fma_f32 v[108:109], v[156:157], v[156:157], v[108:109]
	v_mov_b32_e32 v161, v92
	v_mov_b32_e32 v160, v220
	v_pk_fma_f32 v[108:109], v[158:159], v[158:159], v[108:109]
	v_lshlrev_b32_e32 v66, 16, v14
	v_mov_b32_e32 v163, v93
	v_lshlrev_b32_e32 v194, 16, v78
	v_and_b32_e32 v195, 0xffff0000, v78
	v_lshlrev_b32_e32 v78, 16, v104
	v_mov_b32_e32 v162, v221
	v_pk_fma_f32 v[108:109], v[160:161], v[160:161], v[108:109]
	v_and_b32_e32 v67, 0xffff0000, v14
	v_mov_b32_e32 v165, v66
	v_lshlrev_b32_e32 v196, 16, v79
	v_and_b32_e32 v197, 0xffff0000, v79
	v_and_b32_e32 v79, 0xffff0000, v104
	v_mov_b32_e32 v164, v78
	v_pk_fma_f32 v[108:109], v[162:163], v[162:163], v[108:109]
	v_lshlrev_b32_e32 v68, 16, v15
	v_mov_b32_e32 v167, v67
	v_lshlrev_b32_e32 v198, 16, v80
	v_and_b32_e32 v199, 0xffff0000, v80
	v_lshlrev_b32_e32 v80, 16, v105
	v_mov_b32_e32 v166, v79
	v_pk_fma_f32 v[108:109], v[164:165], v[164:165], v[108:109]
	v_and_b32_e32 v69, 0xffff0000, v15
	v_mov_b32_e32 v169, v68
	v_lshlrev_b32_e32 v200, 16, v81
	v_and_b32_e32 v201, 0xffff0000, v81
	v_and_b32_e32 v81, 0xffff0000, v105
	v_mov_b32_e32 v168, v80
	v_pk_fma_f32 v[108:109], v[166:167], v[166:167], v[108:109]
	v_mov_b32_e32 v175, v69
	v_lshlrev_b32_e32 v82, 16, v106
	v_mov_b32_e32 v174, v81
	v_pk_fma_f32 v[108:109], v[168:169], v[168:169], v[108:109]
	v_mov_b32_e32 v177, v70
	v_and_b32_e32 v83, 0xffff0000, v106
	v_mov_b32_e32 v176, v82
	v_pk_fma_f32 v[108:109], v[174:175], v[174:175], v[108:109]
	v_mov_b32_e32 v179, v71
	v_lshlrev_b32_e32 v84, 16, v107
	v_mov_b32_e32 v178, v83
	v_pk_fma_f32 v[108:109], v[176:177], v[176:177], v[108:109]
	v_mov_b32_e32 v181, v72
	v_and_b32_e32 v85, 0xffff0000, v107
	v_mov_b32_e32 v180, v84
	v_pk_fma_f32 v[108:109], v[178:179], v[178:179], v[108:109]
	v_lshlrev_b32_e32 v14, 16, v10
	v_mov_b32_e32 v183, v73
	v_mov_b32_e32 v182, v85
	v_pk_fma_f32 v[108:109], v[180:181], v[180:181], v[108:109]
	v_and_b32_e32 v15, 0xffff0000, v10
	v_mov_b32_e32 v185, v14
	v_mov_b32_e32 v184, v18
	v_pk_fma_f32 v[108:109], v[182:183], v[182:183], v[108:109]
	v_lshlrev_b32_e32 v10, 16, v11
	v_mov_b32_e32 v187, v15
	v_mov_b32_e32 v186, v19
	v_pk_fma_f32 v[108:109], v[184:185], v[184:185], v[108:109]
	v_and_b32_e32 v11, 0xffff0000, v11
	v_mov_b32_e32 v189, v10
	v_mov_b32_e32 v188, v20
	v_pk_fma_f32 v[108:109], v[186:187], v[186:187], v[108:109]
	v_mov_b32_e32 v193, v11
	v_mov_b32_e32 v192, v21
	v_pk_fma_f32 v[108:109], v[188:189], v[188:189], v[108:109]
	v_lshlrev_b32_e32 v12, 16, v13
	v_and_b32_e32 v13, 0xffff0000, v13
	v_lshlrev_b32_e32 v24, 16, v111
	v_and_b32_e32 v25, 0xffff0000, v111
	v_pk_fma_f32 v[108:109], v[192:193], v[192:193], v[108:109]
	v_pk_mul_f32 v[172:173], v[12:13], v[12:13]
	v_pk_mul_f32 v[110:111], v[24:25], v[24:25]
	v_pk_add_f32 v[108:109], v[202:203], v[108:109]
	v_mov_b32_e32 v205, v172
	v_mov_b32_e32 v204, v110
	v_pk_add_f32 v[108:109], v[170:171], v[108:109]
	v_mov_b32_e32 v172, v111
	v_pk_add_f32 v[108:109], v[204:205], v[108:109]
	v_lshlrev_b32_e32 v104, 16, v114
	v_pk_add_f32 v[108:109], v[172:173], v[108:109]
	ds_bpermute_b32 v111, v1, v109
	ds_bpermute_b32 v110, v1, v108
	v_and_b32_e32 v105, 0xffff0000, v114
	v_lshlrev_b32_e32 v106, 16, v115
	v_and_b32_e32 v107, 0xffff0000, v115
	s_waitcnt lgkmcnt(0)
	v_pk_add_f32 v[108:109], v[108:109], v[110:111]
	ds_bpermute_b32 v111, v61, v109
	ds_bpermute_b32 v110, v61, v108
	s_waitcnt lgkmcnt(0)
	v_pk_add_f32 v[108:109], v[108:109], v[110:111]
	ds_bpermute_b32 v111, v75, v109
	ds_bpermute_b32 v110, v75, v108
	s_waitcnt lgkmcnt(0)
	v_pk_add_f32 v[108:109], v[108:109], v[110:111]
	ds_bpermute_b32 v111, v77, v109
	ds_bpermute_b32 v110, v77, v108
	s_waitcnt lgkmcnt(0)
	v_pk_add_f32 v[108:109], v[108:109], v[110:111]
	ds_bpermute_b32 v111, v94, v109
	ds_bpermute_b32 v110, v94, v108
	s_waitcnt lgkmcnt(0)
	v_pk_add_f32 v[108:109], v[108:109], v[110:111]
	ds_bpermute_b32 v111, v95, v109
	ds_bpermute_b32 v110, v95, v108
	s_waitcnt lgkmcnt(0)
	v_pk_add_f32 v[108:109], v[108:109], v[110:111]
	s_nop 0
	v_pk_fma_f32 v[108:109], v[108:109], s[8:9], v[60:61] op_sel_hi:[1,0,0]
	s_nop 0
	v_mul_f32_e32 v74, 0x4b800000, v109
	v_cmp_gt_f32_e64 s[0:1], s13, v109
	v_mul_f32_e32 v76, 0x4b800000, v108
	v_cmp_gt_f32_e32 vcc, s13, v108
	v_cndmask_b32_e64 v74, v109, v74, s[0:1]
	v_rsq_f32_e32 v74, v74
	v_cndmask_b32_e32 v76, v108, v76, vcc
	v_rsq_f32_e32 v108, v76
	v_mul_f32_e32 v76, 0x45800000, v74
	v_cndmask_b32_e64 v76, v74, v76, s[0:1]
	v_mul_f32_e32 v109, 0x45800000, v108
	v_cndmask_b32_e32 v74, v108, v109, vcc
	v_pk_mul_f32 v[108:109], v[76:77], v[124:125] op_sel_hi:[0,1]
	v_pk_mul_f32 v[110:111], v[76:77], v[126:127] op_sel_hi:[0,1]
	v_pk_mul_f32 v[112:113], v[76:77], v[128:129] op_sel_hi:[0,1]
	v_pk_mul_f32 v[114:115], v[76:77], v[130:131] op_sel_hi:[0,1]
	v_pk_mul_f32 v[124:125], v[74:75], v[206:207] op_sel_hi:[0,1]
	v_pk_mul_f32 v[126:127], v[74:75], v[208:209] op_sel_hi:[0,1]
	v_pk_mul_f32 v[128:129], v[74:75], v[210:211] op_sel_hi:[0,1]
	v_pk_mul_f32 v[130:131], v[74:75], v[212:213] op_sel_hi:[0,1]
	v_pk_mul_f32 v[108:109], v[6:7], v[108:109]
	v_pk_mul_f32 v[110:111], v[8:9], v[110:111]
	v_pk_mul_f32 v[112:113], v[2:3], v[112:113]
	v_pk_mul_f32 v[114:115], v[4:5], v[114:115]
	v_pk_mul_f32 v[124:125], v[6:7], v[124:125]
	v_pk_mul_f32 v[126:127], v[8:9], v[126:127]
	v_pk_mul_f32 v[128:129], v[2:3], v[128:129]
	v_pk_mul_f32 v[130:131], v[4:5], v[130:131]
	v_pk_fma_f32 v[2:3], v[120:121], v[108:109], v[194:195]
	v_pk_fma_f32 v[4:5], v[122:123], v[110:111], v[196:197]
	v_pk_fma_f32 v[6:7], v[116:117], v[112:113], v[198:199]
	v_pk_fma_f32 v[8:9], v[118:119], v[114:115], v[200:201]
	v_pk_fma_f32 v[100:101], v[120:121], v[124:125], v[100:101]
	v_pk_fma_f32 v[102:103], v[122:123], v[126:127], v[102:103]
	v_pk_fma_f32 v[104:105], v[116:117], v[128:129], v[104:105]
	v_pk_fma_f32 v[106:107], v[118:119], v[130:131], v[106:107]
	global_store_dwordx4 v[58:59], v[2:5], off nt
	global_store_dwordx4 v[58:59], v[6:9], off offset:16 nt
	global_store_dwordx4 v[62:63], v[100:103], off offset:-4096 nt
	global_store_dwordx4 v[64:65], v[104:107], off offset:16 nt
	global_load_dwordx4 v[2:5], v[50:51], off offset:2048
	s_nop 0
	global_load_dwordx4 v[6:9], v[50:51], off offset:2064
	global_load_dwordx4 v[100:103], v97, s[10:11]
	global_load_dwordx4 v[104:107], v97, s[10:11] offset:16
	v_pk_mul_f32 v[86:87], v[76:77], v[86:87] op_sel_hi:[0,1]
	v_pk_mul_f32 v[88:89], v[76:77], v[88:89] op_sel_hi:[0,1]
	v_lshlrev_b32_e32 v108, 16, v42
	v_and_b32_e32 v109, 0xffff0000, v42
	v_lshlrev_b32_e32 v42, 16, v43
	v_and_b32_e32 v43, 0xffff0000, v43
	v_pk_mul_f32 v[90:91], v[76:77], v[90:91] op_sel_hi:[0,1]
	v_pk_mul_f32 v[92:93], v[76:77], v[92:93] op_sel_hi:[0,1]
	v_pk_mul_f32 v[116:117], v[74:75], v[214:215] op_sel_hi:[0,1]
	v_pk_mul_f32 v[118:119], v[74:75], v[216:217] op_sel_hi:[0,1]
	v_pk_mul_f32 v[120:121], v[74:75], v[218:219] op_sel_hi:[0,1]
	v_pk_mul_f32 v[122:123], v[74:75], v[220:221] op_sel_hi:[0,1]
	v_lshlrev_b32_e32 v110, 16, v44
	v_and_b32_e32 v111, 0xffff0000, v44
	v_lshlrev_b32_e32 v44, 16, v45
	v_and_b32_e32 v45, 0xffff0000, v45
	v_lshlrev_b32_e32 v112, 16, v46
	v_and_b32_e32 v113, 0xffff0000, v46
	v_lshlrev_b32_e32 v46, 16, v47
	v_and_b32_e32 v47, 0xffff0000, v47
	v_lshlrev_b32_e32 v114, 16, v48
	v_and_b32_e32 v115, 0xffff0000, v48
	v_lshlrev_b32_e32 v48, 16, v49
	v_and_b32_e32 v49, 0xffff0000, v49
	v_pk_mul_f32 v[66:67], v[76:77], v[66:67] op_sel_hi:[0,1]
	v_pk_mul_f32 v[68:69], v[76:77], v[68:69] op_sel_hi:[0,1]
	v_pk_mul_f32 v[70:71], v[76:77], v[70:71] op_sel_hi:[0,1]
	v_pk_mul_f32 v[72:73], v[76:77], v[72:73] op_sel_hi:[0,1]
	v_pk_mul_f32 v[78:79], v[74:75], v[78:79] op_sel_hi:[0,1]
	v_pk_mul_f32 v[80:81], v[74:75], v[80:81] op_sel_hi:[0,1]
	v_pk_mul_f32 v[82:83], v[74:75], v[82:83] op_sel_hi:[0,1]
	v_pk_mul_f32 v[84:85], v[74:75], v[84:85] op_sel_hi:[0,1]
	v_pk_mul_f32 v[14:15], v[76:77], v[14:15] op_sel_hi:[0,1]
	v_pk_mul_f32 v[10:11], v[76:77], v[10:11] op_sel_hi:[0,1]
	v_pk_mul_f32 v[16:17], v[76:77], v[16:17] op_sel_hi:[0,1]
	v_pk_mul_f32 v[12:13], v[76:77], v[12:13] op_sel_hi:[0,1]
	v_pk_mul_f32 v[18:19], v[74:75], v[18:19] op_sel_hi:[0,1]
	v_pk_mul_f32 v[20:21], v[74:75], v[20:21] op_sel_hi:[0,1]
	v_pk_mul_f32 v[22:23], v[74:75], v[22:23] op_sel_hi:[0,1]
	v_pk_mul_f32 v[24:25], v[74:75], v[24:25] op_sel_hi:[0,1]
	s_waitcnt vmcnt(3)
	v_pk_mul_f32 v[86:87], v[2:3], v[86:87]
	v_pk_mul_f32 v[88:89], v[4:5], v[88:89]
	s_waitcnt vmcnt(2)
	v_pk_mul_f32 v[90:91], v[6:7], v[90:91]
	v_pk_mul_f32 v[92:93], v[8:9], v[92:93]
	v_pk_mul_f32 v[116:117], v[2:3], v[116:117]
	v_pk_mul_f32 v[118:119], v[4:5], v[118:119]
	v_pk_mul_f32 v[120:121], v[6:7], v[120:121]
	v_pk_mul_f32 v[122:123], v[8:9], v[122:123]
	s_waitcnt vmcnt(1)
	v_pk_fma_f32 v[2:3], v[100:101], v[86:87], v[108:109]
	v_pk_fma_f32 v[4:5], v[102:103], v[88:89], v[42:43]
	s_waitcnt vmcnt(0)
	v_pk_fma_f32 v[6:7], v[104:105], v[90:91], v[110:111]
	v_pk_fma_f32 v[8:9], v[106:107], v[92:93], v[44:45]
	v_pk_fma_f32 v[42:43], v[100:101], v[116:117], v[112:113]
	v_pk_fma_f32 v[44:45], v[102:103], v[118:119], v[46:47]
	v_pk_fma_f32 v[46:47], v[104:105], v[120:121], v[114:115]
	v_pk_fma_f32 v[48:49], v[106:107], v[122:123], v[48:49]
	global_store_dwordx4 v[58:59], v[2:5], off offset:2048 nt
	global_store_dwordx4 v[58:59], v[6:9], off offset:2064 nt
	global_store_dwordx4 v[64:65], v[42:45], off offset:2048 nt
	global_store_dwordx4 v[64:65], v[46:49], off offset:2064 nt
	global_load_dwordx4 v[2:5], v[52:53], off
	s_nop 0
	global_load_dwordx4 v[6:9], v[52:53], off offset:16
	global_load_dwordx4 v[42:45], v98, s[10:11]
	global_load_dwordx4 v[46:49], v98, s[10:11] offset:16
	v_add_co_u32_e32 v64, vcc, s3, v58
	v_lshlrev_b32_e32 v86, 16, v34
	v_and_b32_e32 v87, 0xffff0000, v34
	v_lshlrev_b32_e32 v34, 16, v35
	v_and_b32_e32 v35, 0xffff0000, v35
	v_addc_co_u32_e32 v65, vcc, 0, v59, vcc
	v_lshlrev_b32_e32 v88, 16, v36
	v_and_b32_e32 v89, 0xffff0000, v36
	v_lshlrev_b32_e32 v36, 16, v37
	v_and_b32_e32 v37, 0xffff0000, v37
	v_lshlrev_b32_e32 v90, 16, v38
	v_and_b32_e32 v91, 0xffff0000, v38
	v_lshlrev_b32_e32 v38, 16, v39
	v_and_b32_e32 v39, 0xffff0000, v39
	v_lshlrev_b32_e32 v92, 16, v40
	v_and_b32_e32 v93, 0xffff0000, v40
	v_lshlrev_b32_e32 v40, 16, v41
	v_and_b32_e32 v41, 0xffff0000, v41
	v_lshl_add_u64 v[58:59], v[58:59], 0, s[6:7]
	s_waitcnt vmcnt(3)
	v_pk_mul_f32 v[66:67], v[2:3], v[66:67]
	v_pk_mul_f32 v[68:69], v[4:5], v[68:69]
	s_waitcnt vmcnt(2)
	v_pk_mul_f32 v[70:71], v[6:7], v[70:71]
	v_pk_mul_f32 v[72:73], v[8:9], v[72:73]
	v_pk_mul_f32 v[78:79], v[2:3], v[78:79]
	v_pk_mul_f32 v[80:81], v[4:5], v[80:81]
	v_pk_mul_f32 v[82:83], v[6:7], v[82:83]
	v_pk_mul_f32 v[84:85], v[8:9], v[84:85]
	s_waitcnt vmcnt(1)
	v_pk_fma_f32 v[2:3], v[42:43], v[66:67], v[86:87]
	v_pk_fma_f32 v[4:5], v[44:45], v[68:69], v[34:35]
	s_waitcnt vmcnt(0)
	v_pk_fma_f32 v[6:7], v[46:47], v[70:71], v[88:89]
	v_pk_fma_f32 v[8:9], v[48:49], v[72:73], v[36:37]
	v_pk_fma_f32 v[34:35], v[42:43], v[78:79], v[90:91]
	v_pk_fma_f32 v[36:37], v[44:45], v[80:81], v[38:39]
	v_pk_fma_f32 v[38:39], v[46:47], v[82:83], v[92:93]
	v_pk_fma_f32 v[40:41], v[48:49], v[84:85], v[40:41]
	global_store_dwordx4 v[64:65], v[2:5], off nt
	global_store_dwordx4 v[64:65], v[6:9], off offset:16 nt
	global_store_dwordx4 v[62:63], v[34:37], off nt
	global_store_dwordx4 v[62:63], v[38:41], off offset:16 nt
	global_load_dwordx4 v[2:5], v[54:55], off
	s_nop 0
	global_load_dwordx4 v[6:9], v[54:55], off offset:16
	global_load_dwordx4 v[34:37], v99, s[10:11]
	global_load_dwordx4 v[38:41], v99, s[10:11] offset:16
	v_lshlrev_b32_e32 v42, 16, v26
	v_and_b32_e32 v43, 0xffff0000, v26
	v_lshlrev_b32_e32 v26, 16, v27
	v_and_b32_e32 v27, 0xffff0000, v27
	v_lshlrev_b32_e32 v44, 16, v28
	v_and_b32_e32 v45, 0xffff0000, v28
	v_lshlrev_b32_e32 v28, 16, v29
	v_and_b32_e32 v29, 0xffff0000, v29
	v_lshlrev_b32_e32 v46, 16, v30
	v_and_b32_e32 v47, 0xffff0000, v30
	v_lshlrev_b32_e32 v30, 16, v31
	v_and_b32_e32 v31, 0xffff0000, v31
	v_lshlrev_b32_e32 v48, 16, v32
	v_and_b32_e32 v49, 0xffff0000, v32
	v_lshlrev_b32_e32 v32, 16, v33
	v_and_b32_e32 v33, 0xffff0000, v33
	s_waitcnt vmcnt(3)
	v_pk_mul_f32 v[14:15], v[14:15], v[2:3]
	v_pk_mul_f32 v[10:11], v[10:11], v[4:5]
	s_waitcnt vmcnt(2)
	v_pk_mul_f32 v[16:17], v[16:17], v[6:7]
	v_pk_mul_f32 v[12:13], v[12:13], v[8:9]
	v_pk_mul_f32 v[18:19], v[2:3], v[18:19]
	v_pk_mul_f32 v[20:21], v[4:5], v[20:21]
	v_pk_mul_f32 v[22:23], v[6:7], v[22:23]
	v_pk_mul_f32 v[24:25], v[8:9], v[24:25]
	s_waitcnt vmcnt(1)
	v_pk_fma_f32 v[2:3], v[14:15], v[34:35], v[42:43]
	v_pk_fma_f32 v[4:5], v[10:11], v[36:37], v[26:27]
	s_waitcnt vmcnt(0)
	v_pk_fma_f32 v[6:7], v[16:17], v[38:39], v[44:45]
	v_pk_fma_f32 v[8:9], v[12:13], v[40:41], v[28:29]
	v_pk_fma_f32 v[10:11], v[34:35], v[18:19], v[46:47]
	v_pk_fma_f32 v[12:13], v[36:37], v[20:21], v[30:31]
	v_pk_fma_f32 v[14:15], v[38:39], v[22:23], v[48:49]
	v_pk_fma_f32 v[16:17], v[40:41], v[24:25], v[32:33]
	global_store_dwordx4 v[64:65], v[2:5], off offset:2048 nt
	global_store_dwordx4 v[64:65], v[6:9], off offset:2064 nt
	global_store_dwordx4 v[62:63], v[10:13], off offset:2048 nt
	global_store_dwordx4 v[62:63], v[14:17], off offset:2064 nt
	v_mov_b32_e32 v1, v222
	v_mov_b32_e32 v138, v223
	v_mov_b32_e32 v139, v224
	v_mov_b32_e32 v140, v225
	v_mov_b32_e32 v141, v226
	v_mov_b32_e32 v142, v227
	v_mov_b32_e32 v143, v228
	v_mov_b32_e32 v144, v229
	v_mov_b32_e32 v145, v230
	v_mov_b32_e32 v154, v231
	v_mov_b32_e32 v155, v232
	v_mov_b32_e32 v156, v233
	v_mov_b32_e32 v157, v234
	v_mov_b32_e32 v158, v235
	v_mov_b32_e32 v159, v236
	v_mov_b32_e32 v160, v237
	v_readlane_b32 s0, v255, 40
	v_readlane_b32 s1, v255, 41
	v_readlane_b32 s2, v255, 42
	v_readlane_b32 s3, v255, 43
	v_readlane_b32 s6, v255, 44
	v_readlane_b32 s7, v255, 45
	v_readlane_b32 s25, v255, 46
	v_readlane_b32 s26, v255, 47
	v_readlane_b32 s27, v255, 48
	v_readlane_b32 s28, v255, 49
	v_readlane_b32 s49, v255, 50
	s_waitcnt vmcnt(0) lgkmcnt(0)
	s_mov_b64 s[8:9], exec
	v_readlane_b32 s10, v254, 2
	v_readlane_b32 s11, v254, 3
	s_nop 1
	s_and_b64 s[10:11], s[8:9], s[10:11]
	s_mov_b64 exec, s[10:11]
	s_cbranch_execz .Llb865_join
	v_mov_b32_e32 v4, 0x23fc4
	ds_read_b32 v3, v4
	s_add_u32 s12, s62, 0x40d000
	s_addc_u32 s13, s63, 0
	v_mov_b32_e32 v4, 0x400
	s_mov_b32 s16, 0
	buffer_inv sc1
.Llb865_spin:
	global_load_dword v17, v4, s[12:13] sc1
	s_waitcnt vmcnt(0) lgkmcnt(0)
	v_cmp_ge_u32_e32 vcc, v17, v3
	s_cbranch_vccnz .Llb865_join
	s_sleep 1
	s_add_u32 s16, s16, 1
	s_cmp_lt_u32 s16, 0x100000
	s_cbranch_scc1 .Llb865_spin

.LBB0_993:
	v_readlane_b32 s14, v254, 39
	s_cmp_lt_i32 s14, 13
	s_cselect_b64 s[2:3], -1, 0
	s_and_b64 s[0:1], s[2:3], s[0:1]
	s_cmpk_lt_i32 s44, 0x2000
	s_cselect_b64 s[2:3], -1, 0
	s_and_b64 s[0:1], s[0:1], s[2:3]
	v_readlane_b32 s15, v254, 40
	s_movk_i32 s9, 0x2000
	s_and_b64 vcc, exec, s[0:1]
	s_cbranch_vccz .LBB0_996
	v_mbcnt_lo_u32_b32 v1, -1, 0
	v_mbcnt_hi_u32_b32 v3, -1, v1
	v_and_b32_e32 v1, 64, v3
	v_add_u32_e32 v4, 64, v1
	v_xor_b32_e32 v1, 1, v3
	v_cmp_lt_i32_e32 vcc, v1, v4
	v_xor_b32_e32 v6, 2, v3
	s_lshl_b32 s2, s44, 1
	v_cndmask_b32_e32 v1, v3, v1, vcc
	v_cmp_lt_i32_e32 vcc, v6, v4
	v_lshlrev_b32_e32 v2, 3, v191
	v_mov_b32_e32 v5, 0
	v_cndmask_b32_e32 v6, v3, v6, vcc
	v_lshlrev_b32_e32 v61, 2, v6
	v_xor_b32_e32 v6, 4, v3
	v_cmp_lt_i32_e32 vcc, v6, v4
	v_or_b32_e32 v8, 0x400, v2
	s_ashr_i32 s3, s2, 31
	v_cndmask_b32_e32 v6, v3, v6, vcc
	v_lshlrev_b32_e32 v75, 2, v6
	v_xor_b32_e32 v6, 8, v3
	v_cmp_lt_i32_e32 vcc, v6, v4
	v_or_b32_e32 v10, 0x600, v2
	v_lshlrev_b32_e32 v12, 2, v8
	v_cndmask_b32_e32 v6, v3, v6, vcc
	v_mov_b32_e32 v13, v5
	s_lshl_b64 s[0:1], s[2:3], 12
	v_lshlrev_b32_e32 v77, 2, v6
	v_xor_b32_e32 v6, 16, v3
	v_lshl_add_u64 v[52:53], s[58:59], 0, v[12:13]
	v_lshlrev_b32_e32 v12, 2, v10
	s_add_u32 s0, s62, s0
	v_cmp_lt_i32_e32 vcc, v6, v4
	v_lshl_add_u64 v[54:55], s[58:59], 0, v[12:13]
	v_lshlrev_b32_e32 v12, 4, v191
	s_addc_u32 s1, s63, s1
	v_cndmask_b32_e32 v6, v3, v6, vcc
	v_lshl_add_u64 v[12:13], s[0:1], 0, v[12:13]
	s_mov_b64 s[0:1], 0x10800000
	s_ashr_i32 s49, s48, 31
	v_lshlrev_b32_e32 v94, 2, v6
	v_xor_b32_e32 v6, 32, v3
	v_lshl_add_u64 v[56:57], v[12:13], 0, s[0:1]
	s_lshl_b64 s[4:5], s[48:49], 12
	s_lshl_b64 s[0:1], s[2:3], 13
	v_cmp_lt_i32_e32 vcc, v6, v4
	s_add_u32 s0, s60, s0
	v_lshlrev_b32_e32 v4, 5, v191
	v_cndmask_b32_e32 v3, v3, v6, vcc
	v_or_b32_e32 v6, 0x200, v2
	s_addc_u32 s1, s61, s1
	v_lshlrev_b32_e32 v1, 2, v1
	v_lshlrev_b32_e32 v95, 2, v3
	v_lshl_add_u64 v[50:51], s[58:59], 0, v[4:5]
	v_lshl_add_u64 v[58:59], s[0:1], 0, v[4:5]
	s_lshl_b64 s[6:7], s[48:49], 13
	s_movk_i32 s3, 0x1000
	s_mov_b32 s12, 0x4001000
	v_lshlrev_b32_e32 v96, 2, v2
	v_lshlrev_b32_e32 v97, 2, v6
	v_lshlrev_b32_e32 v98, 2, v8
	v_lshlrev_b32_e32 v99, 2, v10
	s_mov_b32 s8, 0x3a000000
	s_mov_b32 s13, 0x800000
	s_movk_i32 s14, 0x3000
	v_mov_b32_e32 v60, 0x358637bd
	s_add_i32 s2, s2, s48
	v_lshl_add_u64 v[56:57], v[56:57], 0, s[4:5]
	v_lshl_add_u64 v[58:59], v[58:59], 0, s[6:7]
	s_mov_b32 s20, 0
.LBB0_995:
	s_cmp_lg_u32 s20, 1
	s_cbranch_scc1 .Lr4_nowait
	s_cmp_eq_u32 s21, 0
	s_cbranch_scc1 .Lr4_nowait
	s_mov_b64 s[22:23], exec
	v_readlane_b32 s24, v254, 2
	v_readlane_b32 s25, v254, 3
	s_nop 1
	s_and_b64 s[24:25], s[22:23], s[24:25]
	s_mov_b64 exec, s[24:25]
	s_cbranch_execz .Lr4_wait_join
	v_mov_b32_e32 v2, 0x23fc4
	ds_read_b32 v3, v2
	s_add_u32 s26, s62, 0x408000
	s_addc_u32 s27, s63, 0
	v_mov_b32_e32 v2, 0x400
	s_mov_b32 s28, 0
	buffer_inv sc1
